# v6 + ret_out score-pair bf16 pack by v_cvt_pk_bf16_f32 instead of the software RNE bit trick (16 sites)
# baseline (speedup 1.0000x reference)
; #define LAS __attribute__((address_space(3)))
; __device__ __forceinline__ unsigned pk2(float lo, float hi) { return f2bf(lo) | (f2bf(hi) << 16); }
; __device__ __forceinline__ void ret_out_phase(const Frame& F, const bf16* P0, const bf16* RT, bf16* MIX) {
;     ...
;             float pvv[8];
; #pragma unroll
;             for (int j = 0; j < 4; ++j) { const int sA = 32 * c32 + 4 * fq + j, rA = t - sA, rB = rA - 16;
;                 pvv[j] = rA >= 0 ? s0[j] * exp2f((float)rA * lg) : 0.f; pvv[4 + j] = rB >= 0 ? s1[j] * exp2f((float)rB * lg) : 0.f; }
;             v4u pw; pw.x = pk2(pvv[0], pvv[1]); pw.y = pk2(pvv[2], pvv[3]); pw.z = pk2(pvv[4], pvv[5]); pw.w = pk2(pvv[6], pvv[7]);
;             const bf16x8 pb = __builtin_bit_cast(bf16x8, pw);
; #pragma unroll
;             for (int et = 0; et < 4; ++et) { const LAS bf16* vp = Vt + (16 * et + fr) * VT_LD + 32 * c32 + 4 * fq; const v2u lo = *(const LAS v2u*)vp, hi = *(const LAS v2u*)(vp + 16);
;                 v4u aw; aw.x = lo.x; aw.y = lo.y; aw.z = hi.x; aw.w = hi.y;
;                 ao[et] = __builtin_amdgcn_mfma_f32_16x16x32_bf16(__builtin_bit_cast(bf16x8, aw), pb, ao[et], 0, 0, 0); }
.LBB0_446:
	ds_read_b128 v[38:41], v122 offset:35840
	ds_read_b128 v[42:45], v122 offset:35904
	ds_read_b128 v[46:49], v122 offset:38144
	ds_read_b128 v[50:53], v122 offset:38208
	s_waitcnt lgkmcnt(3)
	v_mfma_f32_16x16x32_bf16 v[38:41], v[38:41], v[34:37], 0
	v_readlane_b32 s72, v254, 5
	s_waitcnt lgkmcnt(1)
	v_mfma_f32_16x16x32_bf16 v[46:49], v[46:49], v[34:37], 0
	v_readlane_b32 s73, v254, 6
	v_mfma_f32_16x16x32_bf16 v[38:41], v[42:45], v[30:33], v[38:41]
	v_mul_f32_e32 v42, v65, v82
	v_exp_f32_e32 v56, v42
	s_waitcnt lgkmcnt(0)
	v_mfma_f32_16x16x32_bf16 v[42:45], v[50:53], v[30:33], v[46:49]
	s_nop 2
	v_mul_f32_e32 v46, v65, v83
	v_exp_f32_e32 v48, v46
	v_mul_f32_e32 v46, v65, v84
	v_exp_f32_e32 v50, v46
	s_nop 0
	v_mul_f32_e32 v46, v65, v85
	v_exp_f32_e32 v52, v46
	v_mov_b32_e32 v46, v56
	v_mul_f32_e32 v49, v65, v86
	v_mul_f32_e32 v53, v65, v87
	v_exp_f32_e32 v49, v49
	v_mul_f32_e32 v55, v65, v88
	v_exp_f32_e32 v53, v53
	v_exp_f32_e32 v55, v55
	v_mov_b32_e32 v47, v49
	v_mov_b32_e32 v49, v53
	v_mov_b32_e32 v51, v55
	v_mov_b32_e32 v55, v40
	v_mov_b32_e32 v40, v39
	v_mul_f32_e32 v57, v65, v89
	v_mov_b32_e32 v54, v38
	v_pk_mul_f32 v[38:39], v[50:51], v[40:41]
	v_exp_f32_e32 v57, v57
	v_cndmask_b32_e64 v50, v38, 0, s[20:21]
	v_cndmask_b32_e64 v51, v39, 0, s[18:19]
	v_mov_b32_e32 v38, v42
	v_mov_b32_e32 v39, v44
	v_pk_mul_f32 v[38:39], v[48:49], v[38:39]
	v_cndmask_b32_e64 v39, 0, v39, s[72:73]
	v_readlane_b32 s72, v254, 9
	v_readlane_b32 s73, v254, 10
	v_mov_b32_e32 v53, v57
	v_mov_b32_e32 v44, v43
	v_cndmask_b32_e64 v38, 0, v38, s[72:73]
	v_readlane_b32 s72, v254, 7
	v_pk_mul_f32 v[40:41], v[52:53], v[44:45]
	v_readlane_b32 s73, v254, 8
	v_pk_mul_f32 v[46:47], v[46:47], v[54:55]
	v_cndmask_b32_e64 v40, 0, v40, s[12:13]
	v_cndmask_b32_e64 v41, 0, v41, s[72:73]
	v_cndmask_b32_e64 v47, v47, 0, s[16:17]
	v_cndmask_b32_e64 v46, v46, 0, s[14:15]
	v_cvt_pk_bf16_f32 v53, v39, v41
	v_cvt_pk_bf16_f32 v52, v38, v40
	ds_read2_b64 v[38:41], v123 offset1:4
	v_cvt_pk_bf16_f32 v50, v46, v50
	v_cvt_pk_bf16_f32 v51, v47, v51
	ds_read2_b64 v[54:57], v127 offset0:96 offset1:100
	s_waitcnt lgkmcnt(1)
	v_mfma_f32_16x16x32_bf16 v[46:49], v[38:41], v[50:53], 0
	ds_read2_b64 v[38:41], v128 offset0:32 offset1:36
	s_waitcnt lgkmcnt(0)
	v_mfma_f32_16x16x32_bf16 v[42:45], v[38:41], v[50:53], 0
	ds_read2_b64 v[38:41], v126 offset0:64 offset1:68
	v_mfma_f32_16x16x32_bf16 v[54:57], v[54:57], v[50:53], 0
	s_waitcnt lgkmcnt(0)
	v_mfma_f32_16x16x32_bf16 v[38:41], v[38:41], v[50:53], 0
	s_nop 5
	v_mov_b32_e32 v50, v54
	v_mov_b32_e32 v51, v55
	v_mov_b32_e32 v52, v56
	v_mov_b32_e32 v53, v57
	s_andn2_b64 vcc, exec, s[92:93]
	s_cbranch_vccnz .LBB0_444
.LBB0_447:
	ds_read_b128 v[50:53], v122 offset:40448
	ds_read_b128 v[130:133], v122 offset:40512
	ds_read_b128 v[134:137], v122 offset:42752
	ds_read_b128 v[138:141], v122 offset:42816
	s_waitcnt lgkmcnt(3)
	v_mfma_f32_16x16x32_bf16 v[50:53], v[50:53], v[34:37], 0
	s_waitcnt lgkmcnt(1)
	v_mfma_f32_16x16x32_bf16 v[134:137], v[134:137], v[34:37], 0
	v_mfma_f32_16x16x32_bf16 v[50:53], v[130:133], v[30:33], v[50:53]
	v_mul_f32_e32 v130, v65, v90
	v_exp_f32_e32 v143, v130
	s_waitcnt lgkmcnt(0)
	v_mfma_f32_16x16x32_bf16 v[130:133], v[138:141], v[30:33], v[134:137]
	v_mul_f32_e32 v141, v65, v96
	s_nop 1
	v_mul_f32_e32 v134, v65, v91
	v_exp_f32_e32 v136, v134
	s_nop 0
	v_mul_f32_e32 v134, v65, v92
	v_exp_f32_e32 v138, v134
	v_mul_f32_e32 v134, v65, v93
	v_exp_f32_e32 v140, v134
	v_mov_b32_e32 v134, v143
	v_mul_f32_e32 v135, v65, v94
	v_exp_f32_e32 v135, v135
	v_cmp_gt_f32_e32 vcc, s1, v141
	v_mul_f32_e32 v139, v65, v95
	v_exp_f32_e32 v139, v139
	v_cndmask_b32_e32 v141, 0, v124, vcc
	v_cndmask_b32_e32 v142, 0, v119, vcc
	v_fmac_f32_e32 v142, v65, v96
	v_exp_f32_e32 v142, v142
	v_mul_f32_e32 v144, v65, v97
	v_exp_f32_e32 v144, v144
	v_mov_b32_e32 v137, v139
	v_ldexp_f32 v139, v142, v141
	v_mov_b32_e32 v141, v144
	v_mov_b32_e32 v143, v52
	v_mov_b32_e32 v52, v51
	v_mov_b32_e32 v142, v50
	v_pk_mul_f32 v[50:51], v[138:139], v[52:53]
	v_pk_mul_f32 v[134:135], v[134:135], v[142:143]
	v_cndmask_b32_e64 v138, v51, 0, s[36:37]
	v_mov_b32_e32 v51, v132
	v_mov_b32_e32 v132, v131
	v_cndmask_b32_e64 v129, v135, 0, s[30:31]
	v_cndmask_b32_e64 v135, v50, 0, s[38:39]
	v_mov_b32_e32 v50, v130
	v_pk_mul_f32 v[52:53], v[140:141], v[132:133]
	v_pk_mul_f32 v[50:51], v[136:137], v[50:51]
	v_cndmask_b32_e64 v52, 0, v52, s[28:29]
	v_cndmask_b32_e64 v53, 0, v53, s[26:27]
	v_cndmask_b32_e64 v134, v134, 0, s[34:35]
	v_cndmask_b32_e64 v51, 0, v51, s[22:23]
	v_cndmask_b32_e64 v50, 0, v50, s[24:25]
	v_cvt_pk_bf16_f32 v133, v51, v53
	v_cvt_pk_bf16_f32 v132, v50, v52
	v_cvt_pk_bf16_f32 v131, v129, v138
	v_cvt_pk_bf16_f32 v130, v134, v135
	ds_read2_b64 v[50:53], v123 offset0:8 offset1:12
	s_waitcnt lgkmcnt(0)
	s_nop 0
	v_mfma_f32_16x16x32_bf16 v[46:49], v[50:53], v[130:133], v[46:49]
	ds_read2_b64 v[50:53], v128 offset0:40 offset1:44
	s_waitcnt lgkmcnt(0)
	v_mfma_f32_16x16x32_bf16 v[42:45], v[50:53], v[130:133], v[42:45]
	ds_read2_b64 v[50:53], v126 offset0:72 offset1:76
	s_waitcnt lgkmcnt(0)
	v_mfma_f32_16x16x32_bf16 v[38:41], v[50:53], v[130:133], v[38:41]
	ds_read2_b64 v[50:53], v127 offset0:104 offset1:108
	s_waitcnt lgkmcnt(0)
	v_mfma_f32_16x16x32_bf16 v[50:53], v[50:53], v[130:133], v[54:57]
	s_andn2_b64 vcc, exec, s[94:95]
	s_cbranch_vccnz .LBB0_445
; #define LAS __attribute__((address_space(3)))
; __device__ __forceinline__ unsigned pk2(float lo, float hi) { return f2bf(lo) | (f2bf(hi) << 16); }
; __device__ __forceinline__ void ret_out_phase(const Frame& F, const bf16* P0, const bf16* RT, bf16* MIX) {
;     ...
;             float pvv[8];
; #pragma unroll
;             for (int j = 0; j < 4; ++j) { const int sA = 32 * c32 + 4 * fq + j, rA = t - sA, rB = rA - 16;
;                 pvv[j] = rA >= 0 ? s0[j] * exp2f((float)rA * lg) : 0.f; pvv[4 + j] = rB >= 0 ? s1[j] * exp2f((float)rB * lg) : 0.f; }
;             v4u pw; pw.x = pk2(pvv[0], pvv[1]); pw.y = pk2(pvv[2], pvv[3]); pw.z = pk2(pvv[4], pvv[5]); pw.w = pk2(pvv[6], pvv[7]);
;             const bf16x8 pb = __builtin_bit_cast(bf16x8, pw);
; #pragma unroll
;             for (int et = 0; et < 4; ++et) { const LAS bf16* vp = Vt + (16 * et + fr) * VT_LD + 32 * c32 + 4 * fq; const v2u lo = *(const LAS v2u*)vp, hi = *(const LAS v2u*)(vp + 16);
;                 v4u aw; aw.x = lo.x; aw.y = lo.y; aw.z = hi.x; aw.w = hi.y;
;                 ao[et] = __builtin_amdgcn_mfma_f32_16x16x32_bf16(__builtin_bit_cast(bf16x8, aw), pb, ao[et], 0, 0, 0); }
.LBB0_448:
	s_nop 0
	ds_read_b128 v[54:57], v122 offset:45056
	ds_read_b128 v[130:133], v122 offset:45120
	ds_read_b128 v[134:137], v122 offset:47360
	ds_read_b128 v[138:141], v122 offset:47424
	s_waitcnt lgkmcnt(3)
	v_mfma_f32_16x16x32_bf16 v[54:57], v[54:57], v[34:37], 0
	s_waitcnt lgkmcnt(1)
	v_mfma_f32_16x16x32_bf16 v[134:137], v[134:137], v[34:37], 0
	v_mfma_f32_16x16x32_bf16 v[54:57], v[130:133], v[30:33], v[54:57]
	v_mul_f32_e32 v130, v65, v98
	v_exp_f32_e32 v143, v130
	s_waitcnt lgkmcnt(0)
	v_mfma_f32_16x16x32_bf16 v[130:133], v[138:141], v[30:33], v[134:137]
	v_mul_f32_e32 v141, v65, v104
	s_nop 1
	v_mul_f32_e32 v134, v65, v99
	v_exp_f32_e32 v136, v134
	s_nop 0
	v_mul_f32_e32 v134, v65, v100
	v_exp_f32_e32 v138, v134
	v_mul_f32_e32 v134, v65, v101
	v_exp_f32_e32 v140, v134
	v_mov_b32_e32 v134, v143
	v_mul_f32_e32 v135, v65, v102
	v_exp_f32_e32 v135, v135
	v_cmp_gt_f32_e32 vcc, s1, v141
	v_mul_f32_e32 v139, v65, v103
	v_exp_f32_e32 v139, v139
	v_cndmask_b32_e32 v141, 0, v124, vcc
	v_cndmask_b32_e32 v142, 0, v119, vcc
	v_fmac_f32_e32 v142, v65, v104
	v_exp_f32_e32 v142, v142
	v_mul_f32_e32 v144, v65, v105
	v_exp_f32_e32 v144, v144
	v_mov_b32_e32 v137, v139
	v_ldexp_f32 v139, v142, v141
	v_mov_b32_e32 v141, v144
	v_mov_b32_e32 v143, v56
	v_mov_b32_e32 v56, v55
	v_mov_b32_e32 v142, v54
	v_pk_mul_f32 v[54:55], v[138:139], v[56:57]
	v_pk_mul_f32 v[134:135], v[134:135], v[142:143]
	v_cndmask_b32_e64 v138, v55, 0, s[52:53]
	v_mov_b32_e32 v55, v132
	v_mov_b32_e32 v132, v131
	v_cndmask_b32_e64 v129, v135, 0, s[48:49]
	v_cndmask_b32_e64 v135, v54, 0, s[54:55]
	v_mov_b32_e32 v54, v130
	v_pk_mul_f32 v[56:57], v[140:141], v[132:133]
	v_pk_mul_f32 v[54:55], v[136:137], v[54:55]
	v_cndmask_b32_e64 v56, 0, v56, s[46:47]
	v_cndmask_b32_e64 v57, 0, v57, s[44:45]
	v_cndmask_b32_e64 v134, v134, 0, s[50:51]
	v_cndmask_b32_e64 v55, 0, v55, s[40:41]
	v_cndmask_b32_e64 v54, 0, v54, s[42:43]
	v_cvt_pk_bf16_f32 v133, v55, v57
	v_cvt_pk_bf16_f32 v132, v54, v56
	v_cvt_pk_bf16_f32 v131, v129, v138
	v_cvt_pk_bf16_f32 v130, v134, v135
	ds_read2_b64 v[54:57], v123 offset0:16 offset1:20
	s_waitcnt lgkmcnt(0)
	s_nop 0
	v_mfma_f32_16x16x32_bf16 v[46:49], v[54:57], v[130:133], v[46:49]
	ds_read2_b64 v[54:57], v128 offset0:48 offset1:52
	s_waitcnt lgkmcnt(0)
	v_mfma_f32_16x16x32_bf16 v[42:45], v[54:57], v[130:133], v[42:45]
	ds_read2_b64 v[54:57], v126 offset0:80 offset1:84
	s_waitcnt lgkmcnt(0)
	v_mfma_f32_16x16x32_bf16 v[38:41], v[54:57], v[130:133], v[38:41]
	ds_read2_b64 v[54:57], v127 offset0:112 offset1:116
	s_waitcnt lgkmcnt(0)
	v_mfma_f32_16x16x32_bf16 v[50:53], v[54:57], v[130:133], v[50:53]
	s_andn2_b64 vcc, exec, s[96:97]
	s_lshl_b32 s11, s11, 6
	s_cbranch_vccnz .LBB0_439
.LBB0_449:
	ds_read_b128 v[54:57], v122 offset:49664
	ds_read_b128 v[128:131], v122 offset:49728
	ds_read_b128 v[132:135], v122 offset:51968
	ds_read_b128 v[136:139], v122 offset:52032
	s_waitcnt lgkmcnt(3)
	v_mfma_f32_16x16x32_bf16 v[54:57], v[54:57], v[34:37], 0
	s_waitcnt lgkmcnt(1)
	v_mfma_f32_16x16x32_bf16 v[132:135], v[132:135], v[34:37], 0
	v_mfma_f32_16x16x32_bf16 v[54:57], v[128:131], v[30:33], v[54:57]
	v_mul_f32_e32 v128, v65, v106
	v_exp_f32_e32 v141, v128
	s_waitcnt lgkmcnt(0)
	v_mfma_f32_16x16x32_bf16 v[128:131], v[136:139], v[30:33], v[132:135]
	v_mul_f32_e32 v139, v65, v112
	s_nop 1
	v_mul_f32_e32 v132, v65, v107
	v_exp_f32_e32 v134, v132
	s_nop 0
	v_mul_f32_e32 v132, v65, v108
	v_exp_f32_e32 v136, v132
	v_mul_f32_e32 v132, v65, v109
	v_exp_f32_e32 v138, v132
	v_mov_b32_e32 v132, v141
	v_mul_f32_e32 v133, v65, v110
	v_exp_f32_e32 v133, v133
	v_cmp_gt_f32_e32 vcc, s1, v139
	v_mul_f32_e32 v137, v65, v111
	v_exp_f32_e32 v137, v137
	v_cndmask_b32_e32 v139, 0, v124, vcc
	v_cndmask_b32_e32 v140, 0, v119, vcc
	v_fmac_f32_e32 v140, v65, v112
	v_exp_f32_e32 v140, v140
	v_mul_f32_e32 v142, v65, v113
	v_exp_f32_e32 v142, v142
	v_mov_b32_e32 v135, v137
	v_ldexp_f32 v137, v140, v139
	v_mov_b32_e32 v139, v142
	v_mov_b32_e32 v141, v56
	v_mov_b32_e32 v56, v55
	v_mov_b32_e32 v140, v54
	v_pk_mul_f32 v[54:55], v[136:137], v[56:57]
	v_pk_mul_f32 v[132:133], v[132:133], v[140:141]
	v_cndmask_b32_e64 v136, v55, 0, s[68:69]
	v_mov_b32_e32 v55, v130
	v_mov_b32_e32 v130, v129
	v_cndmask_b32_e64 v127, v133, 0, s[64:65]
	v_cndmask_b32_e64 v133, v54, 0, s[70:71]
	v_mov_b32_e32 v54, v128
	v_pk_mul_f32 v[56:57], v[138:139], v[130:131]
	v_pk_mul_f32 v[54:55], v[134:135], v[54:55]
	v_cndmask_b32_e64 v56, 0, v56, s[62:63]
	v_cndmask_b32_e64 v57, 0, v57, s[60:61]
	v_cndmask_b32_e64 v132, v132, 0, s[66:67]
	v_cndmask_b32_e64 v55, 0, v55, s[56:57]
	v_cndmask_b32_e64 v54, 0, v54, s[58:59]
	v_cvt_pk_bf16_f32 v131, v55, v57
	v_cvt_pk_bf16_f32 v130, v54, v56
	v_cvt_pk_bf16_f32 v129, v127, v136
	v_cvt_pk_bf16_f32 v128, v132, v133
	ds_read2_b64 v[54:57], v123 offset0:24 offset1:28
	s_waitcnt lgkmcnt(0)
	s_nop 0
	v_mfma_f32_16x16x32_bf16 v[46:49], v[54:57], v[128:131], v[46:49]
	ds_read2_b64 v[54:57], v115 offset0:24 offset1:28
	s_waitcnt lgkmcnt(0)
	v_mfma_f32_16x16x32_bf16 v[42:45], v[54:57], v[128:131], v[42:45]
	ds_read2_b64 v[54:57], v126 offset0:88 offset1:92
	s_waitcnt lgkmcnt(0)
	v_mfma_f32_16x16x32_bf16 v[38:41], v[54:57], v[128:131], v[38:41]
	v_add_u32_e32 v54, 0x2000, v115
	ds_read2_b64 v[54:57], v54 offset0:88 offset1:92
	s_waitcnt lgkmcnt(0)
	v_mfma_f32_16x16x32_bf16 v[50:53], v[54:57], v[128:131], v[50:53]
	s_branch .LBB0_439
